# straight-line widened-store epilogue fast paths for P7 projection units (pn>=12) and P1 which==0 units
# speedup vs baseline: 1.2117x; 1.0123x over previous
.LBB0_210:
	s_cmp_lg_u32 s96, 0
	s_cbranch_scc1 .Lp1_epi_other
	v_lshl_add_u32 v2, s60, 8, v224
	s_waitcnt lgkmcnt(0)
	s_mov_b64 s[6:7], 0x100000
	v_lshl_or_b32 v132, s56, 8, v234
	v_bfe_u32 v138, v234, 2, 1
	v_mul_u32_u24_e32 v138, 24, v138
	v_lshl_add_u32 v136, v132, 1, v138
	v_mov_b32_e32 v137, 0
	v_ashrrev_i32_e32 v3, 31, v2
	v_lshlrev_b64 v[140:141], 13, v[2:3]
	v_lshl_add_u64 v[140:141], s[26:27], 0, v[140:141]
	v_lshl_add_u64 v[140:141], v[140:141], 0, v[136:137]
	v_or_b32_e32 v142, 16, v2
	v_ashrrev_i32_e32 v143, 31, v142
	v_lshlrev_b64 v[142:143], 13, v[142:143]
	v_lshl_add_u64 v[142:143], s[26:27], 0, v[142:143]
	v_lshl_add_u64 v[142:143], v[142:143], 0, v[136:137]
	v_or_b32_e32 v144, 32, v2
	v_ashrrev_i32_e32 v145, 31, v144
	v_lshlrev_b64 v[144:145], 13, v[144:145]
	v_lshl_add_u64 v[144:145], s[26:27], 0, v[144:145]
	v_lshl_add_u64 v[144:145], v[144:145], 0, v[136:137]
	v_or_b32_e32 v146, 48, v2
	v_ashrrev_i32_e32 v147, 31, v146
	v_lshlrev_b64 v[146:147], 13, v[146:147]
	v_lshl_add_u64 v[146:147], s[26:27], 0, v[146:147]
	v_lshl_add_u64 v[146:147], v[146:147], 0, v[136:137]
	v_lshl_add_u64 v[148:149], v[140:141], 0, s[6:7]
	v_lshl_add_u64 v[150:151], v[142:143], 0, s[6:7]
	v_lshl_add_u64 v[152:153], v[144:145], 0, s[6:7]
	v_lshl_add_u64 v[154:155], v[146:147], 0, s[6:7]
	s_nop 7
	v_cvt_pk_bf16_f32 v128, v128, v129
	v_cvt_pk_bf16_f32 v129, v130, v131
	v_cvt_pk_bf16_f32 v130, v124, v125
	v_cvt_pk_bf16_f32 v131, v126, v127
	v_cvt_pk_bf16_f32 v120, v120, v121
	v_cvt_pk_bf16_f32 v121, v122, v123
	v_cvt_pk_bf16_f32 v122, v116, v117
	v_cvt_pk_bf16_f32 v123, v118, v119
	s_nop 1
	v_permlane16_swap_b32_e32 v128, v130
	v_permlane16_swap_b32_e32 v129, v131
	v_permlane16_swap_b32_e32 v120, v122
	v_permlane16_swap_b32_e32 v121, v123
	global_store_dwordx4 v[140:141], v[128:131], off
	global_store_dwordx4 v[140:141], v[120:123], off offset:256
	v_cvt_pk_bf16_f32 v112, v112, v113
	v_cvt_pk_bf16_f32 v113, v114, v115
	v_cvt_pk_bf16_f32 v114, v108, v109
	v_cvt_pk_bf16_f32 v115, v110, v111
	v_cvt_pk_bf16_f32 v104, v104, v105
	v_cvt_pk_bf16_f32 v105, v106, v107
	v_cvt_pk_bf16_f32 v106, v100, v101
	v_cvt_pk_bf16_f32 v107, v102, v103
	s_nop 1
	v_permlane16_swap_b32_e32 v112, v114
	v_permlane16_swap_b32_e32 v113, v115
	v_permlane16_swap_b32_e32 v104, v106
	v_permlane16_swap_b32_e32 v105, v107
	global_store_dwordx4 v[142:143], v[112:115], off
	global_store_dwordx4 v[142:143], v[104:107], off offset:256
	v_cvt_pk_bf16_f32 v96, v96, v97
	v_cvt_pk_bf16_f32 v97, v98, v99
	v_cvt_pk_bf16_f32 v98, v92, v93
	v_cvt_pk_bf16_f32 v99, v94, v95
	v_cvt_pk_bf16_f32 v88, v88, v89
	v_cvt_pk_bf16_f32 v89, v90, v91
	v_cvt_pk_bf16_f32 v90, v84, v85
	v_cvt_pk_bf16_f32 v91, v86, v87
	s_nop 1
	v_permlane16_swap_b32_e32 v96, v98
	v_permlane16_swap_b32_e32 v97, v99
	v_permlane16_swap_b32_e32 v88, v90
	v_permlane16_swap_b32_e32 v89, v91
	global_store_dwordx4 v[144:145], v[96:99], off
	global_store_dwordx4 v[144:145], v[88:91], off offset:256
	v_cvt_pk_bf16_f32 v80, v80, v81
	v_cvt_pk_bf16_f32 v81, v82, v83
	v_cvt_pk_bf16_f32 v82, v76, v77
	v_cvt_pk_bf16_f32 v83, v78, v79
	v_cvt_pk_bf16_f32 v72, v72, v73
	v_cvt_pk_bf16_f32 v73, v74, v75
	v_cvt_pk_bf16_f32 v74, v68, v69
	v_cvt_pk_bf16_f32 v75, v70, v71
	s_nop 1
	v_permlane16_swap_b32_e32 v80, v82
	v_permlane16_swap_b32_e32 v81, v83
	v_permlane16_swap_b32_e32 v72, v74
	v_permlane16_swap_b32_e32 v73, v75
	global_store_dwordx4 v[146:147], v[80:83], off
	global_store_dwordx4 v[146:147], v[72:75], off offset:256
	v_cvt_pk_bf16_f32 v64, v64, v65
	v_cvt_pk_bf16_f32 v65, v66, v67
	v_cvt_pk_bf16_f32 v66, v60, v61
	v_cvt_pk_bf16_f32 v67, v62, v63
	v_cvt_pk_bf16_f32 v56, v56, v57
	v_cvt_pk_bf16_f32 v57, v58, v59
	v_cvt_pk_bf16_f32 v58, v52, v53
	v_cvt_pk_bf16_f32 v59, v54, v55
	s_nop 1
	v_permlane16_swap_b32_e32 v64, v66
	v_permlane16_swap_b32_e32 v65, v67
	v_permlane16_swap_b32_e32 v56, v58
	v_permlane16_swap_b32_e32 v57, v59
	global_store_dwordx4 v[148:149], v[64:67], off
	global_store_dwordx4 v[148:149], v[56:59], off offset:256
	v_cvt_pk_bf16_f32 v48, v48, v49
	v_cvt_pk_bf16_f32 v49, v50, v51
	v_cvt_pk_bf16_f32 v50, v44, v45
	v_cvt_pk_bf16_f32 v51, v46, v47
	v_cvt_pk_bf16_f32 v40, v40, v41
	v_cvt_pk_bf16_f32 v41, v42, v43
	v_cvt_pk_bf16_f32 v42, v36, v37
	v_cvt_pk_bf16_f32 v43, v38, v39
	s_nop 1
	v_permlane16_swap_b32_e32 v48, v50
	v_permlane16_swap_b32_e32 v49, v51
	v_permlane16_swap_b32_e32 v40, v42
	v_permlane16_swap_b32_e32 v41, v43
	global_store_dwordx4 v[150:151], v[48:51], off
	global_store_dwordx4 v[150:151], v[40:43], off offset:256
	v_cvt_pk_bf16_f32 v32, v32, v33
	v_cvt_pk_bf16_f32 v33, v34, v35
	v_cvt_pk_bf16_f32 v34, v28, v29
	v_cvt_pk_bf16_f32 v35, v30, v31
	v_cvt_pk_bf16_f32 v24, v24, v25
	v_cvt_pk_bf16_f32 v25, v26, v27
	v_cvt_pk_bf16_f32 v26, v20, v21
	v_cvt_pk_bf16_f32 v27, v22, v23
	s_nop 1
	v_permlane16_swap_b32_e32 v32, v34
	v_permlane16_swap_b32_e32 v33, v35
	v_permlane16_swap_b32_e32 v24, v26
	v_permlane16_swap_b32_e32 v25, v27
	global_store_dwordx4 v[152:153], v[32:35], off
	global_store_dwordx4 v[152:153], v[24:27], off offset:256
	v_cvt_pk_bf16_f32 v16, v16, v17
	v_cvt_pk_bf16_f32 v17, v18, v19
	v_cvt_pk_bf16_f32 v18, v12, v13
	v_cvt_pk_bf16_f32 v19, v14, v15
	v_cvt_pk_bf16_f32 v8, v8, v9
	v_cvt_pk_bf16_f32 v9, v10, v11
	v_cvt_pk_bf16_f32 v10, v4, v5
	v_cvt_pk_bf16_f32 v11, v6, v7
	s_nop 1
	v_permlane16_swap_b32_e32 v16, v18
	v_permlane16_swap_b32_e32 v17, v19
	v_permlane16_swap_b32_e32 v8, v10
	v_permlane16_swap_b32_e32 v9, v11
	global_store_dwordx4 v[154:155], v[16:19], off
	global_store_dwordx4 v[154:155], v[8:11], off offset:256
	s_branch .LBB0_187

.LBB0_555:
	s_waitcnt lgkmcnt(0)
	s_cmp_lt_u32 s58, 12
	s_cbranch_scc1 .Lp7_epi_kv
	v_lshl_add_u32 v2, s10, 8, v240
	s_mov_b64 s[12:13], 0x100000
	v_lshl_or_b32 v132, s58, 8, v242
	v_bfe_u32 v138, v242, 2, 1
	v_mul_u32_u24_e32 v138, 24, v138
	v_lshl_add_u32 v136, v132, 1, v138
	v_subrev_u32_e32 v136, 6144, v136
	v_mov_b32_e32 v137, 0
	v_ashrrev_i32_e32 v3, 31, v2
	v_lshlrev_b64 v[140:141], 13, v[2:3]
	v_lshl_add_u64 v[140:141], s[26:27], 0, v[140:141]
	v_lshl_add_u64 v[140:141], v[140:141], 0, v[136:137]
	v_or_b32_e32 v142, 16, v2
	v_ashrrev_i32_e32 v143, 31, v142
	v_lshlrev_b64 v[142:143], 13, v[142:143]
	v_lshl_add_u64 v[142:143], s[26:27], 0, v[142:143]
	v_lshl_add_u64 v[142:143], v[142:143], 0, v[136:137]
	v_or_b32_e32 v144, 32, v2
	v_ashrrev_i32_e32 v145, 31, v144
	v_lshlrev_b64 v[144:145], 13, v[144:145]
	v_lshl_add_u64 v[144:145], s[26:27], 0, v[144:145]
	v_lshl_add_u64 v[144:145], v[144:145], 0, v[136:137]
	v_or_b32_e32 v146, 48, v2
	v_ashrrev_i32_e32 v147, 31, v146
	v_lshlrev_b64 v[146:147], 13, v[146:147]
	v_lshl_add_u64 v[146:147], s[26:27], 0, v[146:147]
	v_lshl_add_u64 v[146:147], v[146:147], 0, v[136:137]
	v_lshl_add_u64 v[148:149], v[140:141], 0, s[12:13]
	v_lshl_add_u64 v[150:151], v[142:143], 0, s[12:13]
	v_lshl_add_u64 v[152:153], v[144:145], 0, s[12:13]
	v_lshl_add_u64 v[154:155], v[146:147], 0, s[12:13]
	s_nop 7
	v_cvt_pk_bf16_f32 v128, v128, v129
	v_cvt_pk_bf16_f32 v129, v130, v131
	v_cvt_pk_bf16_f32 v130, v124, v125
	v_cvt_pk_bf16_f32 v131, v126, v127
	v_cvt_pk_bf16_f32 v120, v120, v121
	v_cvt_pk_bf16_f32 v121, v122, v123
	v_cvt_pk_bf16_f32 v122, v116, v117
	v_cvt_pk_bf16_f32 v123, v118, v119
	s_nop 1
	v_permlane16_swap_b32_e32 v128, v130
	v_permlane16_swap_b32_e32 v129, v131
	v_permlane16_swap_b32_e32 v120, v122
	v_permlane16_swap_b32_e32 v121, v123
	global_store_dwordx4 v[140:141], v[128:131], off
	global_store_dwordx4 v[140:141], v[120:123], off offset:256
	v_cvt_pk_bf16_f32 v112, v112, v113
	v_cvt_pk_bf16_f32 v113, v114, v115
	v_cvt_pk_bf16_f32 v114, v108, v109
	v_cvt_pk_bf16_f32 v115, v110, v111
	v_cvt_pk_bf16_f32 v104, v104, v105
	v_cvt_pk_bf16_f32 v105, v106, v107
	v_cvt_pk_bf16_f32 v106, v100, v101
	v_cvt_pk_bf16_f32 v107, v102, v103
	s_nop 1
	v_permlane16_swap_b32_e32 v112, v114
	v_permlane16_swap_b32_e32 v113, v115
	v_permlane16_swap_b32_e32 v104, v106
	v_permlane16_swap_b32_e32 v105, v107
	global_store_dwordx4 v[142:143], v[112:115], off
	global_store_dwordx4 v[142:143], v[104:107], off offset:256
	v_cvt_pk_bf16_f32 v96, v96, v97
	v_cvt_pk_bf16_f32 v97, v98, v99
	v_cvt_pk_bf16_f32 v98, v92, v93
	v_cvt_pk_bf16_f32 v99, v94, v95
	v_cvt_pk_bf16_f32 v88, v88, v89
	v_cvt_pk_bf16_f32 v89, v90, v91
	v_cvt_pk_bf16_f32 v90, v84, v85
	v_cvt_pk_bf16_f32 v91, v86, v87
	s_nop 1
	v_permlane16_swap_b32_e32 v96, v98
	v_permlane16_swap_b32_e32 v97, v99
	v_permlane16_swap_b32_e32 v88, v90
	v_permlane16_swap_b32_e32 v89, v91
	global_store_dwordx4 v[144:145], v[96:99], off
	global_store_dwordx4 v[144:145], v[88:91], off offset:256
	v_cvt_pk_bf16_f32 v80, v80, v81
	v_cvt_pk_bf16_f32 v81, v82, v83
	v_cvt_pk_bf16_f32 v82, v76, v77
	v_cvt_pk_bf16_f32 v83, v78, v79
	v_cvt_pk_bf16_f32 v72, v72, v73
	v_cvt_pk_bf16_f32 v73, v74, v75
	v_cvt_pk_bf16_f32 v74, v68, v69
	v_cvt_pk_bf16_f32 v75, v70, v71
	s_nop 1
	v_permlane16_swap_b32_e32 v80, v82
	v_permlane16_swap_b32_e32 v81, v83
	v_permlane16_swap_b32_e32 v72, v74
	v_permlane16_swap_b32_e32 v73, v75
	global_store_dwordx4 v[146:147], v[80:83], off
	global_store_dwordx4 v[146:147], v[72:75], off offset:256
	v_cvt_pk_bf16_f32 v64, v64, v65
	v_cvt_pk_bf16_f32 v65, v66, v67
	v_cvt_pk_bf16_f32 v66, v60, v61
	v_cvt_pk_bf16_f32 v67, v62, v63
	v_cvt_pk_bf16_f32 v56, v56, v57
	v_cvt_pk_bf16_f32 v57, v58, v59
	v_cvt_pk_bf16_f32 v58, v52, v53
	v_cvt_pk_bf16_f32 v59, v54, v55
	s_nop 1
	v_permlane16_swap_b32_e32 v64, v66
	v_permlane16_swap_b32_e32 v65, v67
	v_permlane16_swap_b32_e32 v56, v58
	v_permlane16_swap_b32_e32 v57, v59
	global_store_dwordx4 v[148:149], v[64:67], off
	global_store_dwordx4 v[148:149], v[56:59], off offset:256
	v_cvt_pk_bf16_f32 v48, v48, v49
	v_cvt_pk_bf16_f32 v49, v50, v51
	v_cvt_pk_bf16_f32 v50, v44, v45
	v_cvt_pk_bf16_f32 v51, v46, v47
	v_cvt_pk_bf16_f32 v40, v40, v41
	v_cvt_pk_bf16_f32 v41, v42, v43
	v_cvt_pk_bf16_f32 v42, v36, v37
	v_cvt_pk_bf16_f32 v43, v38, v39
	s_nop 1
	v_permlane16_swap_b32_e32 v48, v50
	v_permlane16_swap_b32_e32 v49, v51
	v_permlane16_swap_b32_e32 v40, v42
	v_permlane16_swap_b32_e32 v41, v43
	global_store_dwordx4 v[150:151], v[48:51], off
	global_store_dwordx4 v[150:151], v[40:43], off offset:256
	v_cvt_pk_bf16_f32 v32, v32, v33
	v_cvt_pk_bf16_f32 v33, v34, v35
	v_cvt_pk_bf16_f32 v34, v28, v29
	v_cvt_pk_bf16_f32 v35, v30, v31
	v_cvt_pk_bf16_f32 v24, v24, v25
	v_cvt_pk_bf16_f32 v25, v26, v27
	v_cvt_pk_bf16_f32 v26, v20, v21
	v_cvt_pk_bf16_f32 v27, v22, v23
	s_nop 1
	v_permlane16_swap_b32_e32 v32, v34
	v_permlane16_swap_b32_e32 v33, v35
	v_permlane16_swap_b32_e32 v24, v26
	v_permlane16_swap_b32_e32 v25, v27
	global_store_dwordx4 v[152:153], v[32:35], off
	global_store_dwordx4 v[152:153], v[24:27], off offset:256
	v_cvt_pk_bf16_f32 v16, v16, v17
	v_cvt_pk_bf16_f32 v17, v18, v19
	v_cvt_pk_bf16_f32 v18, v12, v13
	v_cvt_pk_bf16_f32 v19, v14, v15
	v_cvt_pk_bf16_f32 v8, v8, v9
	v_cvt_pk_bf16_f32 v9, v10, v11
	v_cvt_pk_bf16_f32 v10, v4, v5
	v_cvt_pk_bf16_f32 v11, v6, v7
	s_nop 1
	v_permlane16_swap_b32_e32 v16, v18
	v_permlane16_swap_b32_e32 v17, v19
	v_permlane16_swap_b32_e32 v8, v10
	v_permlane16_swap_b32_e32 v9, v11
	global_store_dwordx4 v[154:155], v[16:19], off
	global_store_dwordx4 v[154:155], v[8:11], off offset:256
	s_mov_b64 s[8:9], exec
	s_branch .LBB0_534
.Lp7_epi_kv:
	v_lshl_add_u32 v132, s10, 8, v240
	v_add_u32_e32 v1, 0xffffc000, v132
	v_lshrrev_b32_e32 v3, 4, v1
	v_mad_u64_u32 v[134:135], s[8:9], v3, s81, v[214:215]
	v_mad_u64_u32 v[136:137], s[8:9], v134, s82, 0
	v_mov_b32_e32 v134, v137
	v_mad_u64_u32 v[134:135], s[8:9], v135, s82, v[134:135]
	v_lshl_or_b32 v2, s58, 8, v242
	v_mad_u64_u32 v[138:139], s[8:9], v1, s80, 0
	v_mov_b32_e32 v137, v134
	v_mad_i64_i32 v[134:135], s[8:9], v132, s83, 0
	v_cmp_gt_i32_e64 s[18:19], s78, v132
	v_cmp_lt_i32_e64 s[16:17], s79, v132
	v_cmp_gt_i32_e64 s[8:9], s82, v2
	s_and_saveexec_b64 s[10:11], s[8:9]
	s_xor_b64 s[10:11], exec, s[10:11]
	s_cbranch_execz .LBB0_562
	s_and_saveexec_b64 s[12:13], s[18:19]
	s_cbranch_execz .LBB0_561
	v_cmp_lt_i32_e32 vcc, s84, v2
	v_cvt_pk_bf16_f32 v142, v128, v129
	v_cvt_pk_bf16_f32 v143, v130, v131
	v_cndmask_b32_e32 v1, 0, v247, vcc
	v_add_u32_e32 v140, v1, v2
	v_ashrrev_i32_e32 v141, 31, v140
	s_and_saveexec_b64 s[14:15], s[16:17]
	s_xor_b64 s[14:15], exec, s[14:15]
	s_cbranch_execz .LBB0_559
	v_cndmask_b32_e32 v144, v248, v249, vcc
	v_mov_b32_e32 v145, v0
	v_lshl_add_u64 v[144:145], s[48:49], 0, v[144:145]
	v_lshl_add_u64 v[144:145], v[144:145], 0, v[138:139]
	v_lshl_add_u64 v[144:145], v[140:141], 2, v[144:145]
	v_mov_b32_e32 v1, s31
	v_mov_b32_e32 v3, s21
	global_store_dwordx4 v[144:145], v[128:131], off
	v_cndmask_b32_e32 v145, v1, v3, vcc
	v_mov_b32_e32 v1, s30
	v_mov_b32_e32 v3, s20
	v_cndmask_b32_e32 v144, v1, v3, vcc
	v_lshl_add_u64 v[144:145], v[144:145], 0, v[136:137]
	v_lshl_add_u64 v[140:141], v[140:141], 1, v[144:145]
	global_store_dwordx2 v[140:141], v[142:143], off
